# adds E9: second-half residual loads issue without waiting for first-half stores (stacked on E1,E4,E5,E6,E7,E8)
# speedup vs baseline: 1.0020x; 1.0020x over previous
.LBB0_463:
	v_ashrrev_i32_e32 v133, 31, v132
	v_ashrrev_i32_e32 v131, 31, v130
	v_lshlrev_b64 v[72:73], 11, v[132:133]
	v_lshlrev_b64 v[80:81], 11, v[130:131]
	v_lshl_add_u64 v[68:69], v[136:137], 1, v[218:219]
	v_lshl_add_u64 v[76:77], v[218:219], 0, v[72:73]
	v_lshl_add_u64 v[84:85], v[218:219], 0, v[80:81]
	v_ashrrev_i32_e32 v129, 31, v128
	global_load_dwordx4 v[64:67], v[68:69], off
	s_nop 0
	global_load_dwordx4 v[68:71], v[68:69], off offset:256
	s_nop 0
	global_load_dwordx4 v[72:75], v[76:77], off
	s_nop 0
	global_load_dwordx4 v[76:79], v[76:77], off offset:256
	s_nop 0
	global_load_dwordx4 v[80:83], v[84:85], off
	global_load_dwordx4 v[138:141], v[84:85], off offset:256
	v_lshlrev_b64 v[84:85], 11, v[128:129]
	v_lshl_add_u64 v[84:85], v[218:219], 0, v[84:85]
	global_load_dwordx4 v[142:145], v[84:85], off
	global_load_dwordx4 v[146:149], v[84:85], off offset:256
	s_waitcnt vmcnt(7)
	v_lshlrev_b32_e32 v124, 16, v64
	v_and_b32_e32 v125, 0xffff0000, v64
	v_lshlrev_b32_e32 v126, 16, v65
	v_and_b32_e32 v127, 0xffff0000, v65
	v_lshlrev_b32_e32 v120, 16, v66
	v_and_b32_e32 v121, 0xffff0000, v66
	v_lshlrev_b32_e32 v122, 16, v67
	v_and_b32_e32 v123, 0xffff0000, v67
	s_waitcnt vmcnt(6)
	v_lshlrev_b32_e32 v116, 16, v68
	v_and_b32_e32 v117, 0xffff0000, v68
	v_lshlrev_b32_e32 v118, 16, v69
	v_and_b32_e32 v119, 0xffff0000, v69
	v_lshlrev_b32_e32 v112, 16, v70
	v_and_b32_e32 v113, 0xffff0000, v70
	v_lshlrev_b32_e32 v114, 16, v71
	v_and_b32_e32 v115, 0xffff0000, v71
	s_waitcnt vmcnt(5)
	v_lshlrev_b32_e32 v108, 16, v72
	v_and_b32_e32 v109, 0xffff0000, v72
	v_lshlrev_b32_e32 v110, 16, v73
	v_and_b32_e32 v111, 0xffff0000, v73
	v_lshlrev_b32_e32 v104, 16, v74
	v_and_b32_e32 v105, 0xffff0000, v74
	v_lshlrev_b32_e32 v106, 16, v75
	v_and_b32_e32 v107, 0xffff0000, v75
	s_waitcnt vmcnt(4)
	v_lshlrev_b32_e32 v100, 16, v76
	v_and_b32_e32 v101, 0xffff0000, v76
	v_lshlrev_b32_e32 v102, 16, v77
	v_and_b32_e32 v103, 0xffff0000, v77
	v_lshlrev_b32_e32 v96, 16, v78
	v_and_b32_e32 v97, 0xffff0000, v78
	v_lshlrev_b32_e32 v98, 16, v79
	v_and_b32_e32 v99, 0xffff0000, v79
	s_waitcnt vmcnt(3)
	v_lshlrev_b32_e32 v92, 16, v80
	v_and_b32_e32 v93, 0xffff0000, v80
	v_lshlrev_b32_e32 v94, 16, v81
	v_and_b32_e32 v95, 0xffff0000, v81
	v_lshlrev_b32_e32 v88, 16, v82
	v_and_b32_e32 v89, 0xffff0000, v82
	v_lshlrev_b32_e32 v90, 16, v83
	v_and_b32_e32 v91, 0xffff0000, v83
	s_waitcnt vmcnt(2)
	v_lshlrev_b32_e32 v84, 16, v138
	v_and_b32_e32 v85, 0xffff0000, v138
	v_lshlrev_b32_e32 v86, 16, v139
	v_and_b32_e32 v87, 0xffff0000, v139
	v_lshlrev_b32_e32 v80, 16, v140
	v_and_b32_e32 v81, 0xffff0000, v140
	v_lshlrev_b32_e32 v82, 16, v141
	v_and_b32_e32 v83, 0xffff0000, v141
	s_waitcnt vmcnt(1)
	v_lshlrev_b32_e32 v76, 16, v142
	v_and_b32_e32 v77, 0xffff0000, v142
	v_lshlrev_b32_e32 v78, 16, v143
	v_and_b32_e32 v79, 0xffff0000, v143
	v_lshlrev_b32_e32 v72, 16, v144
	v_and_b32_e32 v73, 0xffff0000, v144
	v_lshlrev_b32_e32 v74, 16, v145
	v_and_b32_e32 v75, 0xffff0000, v145
	s_waitcnt vmcnt(0)
	v_lshlrev_b32_e32 v68, 16, v146
	v_and_b32_e32 v69, 0xffff0000, v146
	v_lshlrev_b32_e32 v70, 16, v147
	v_and_b32_e32 v71, 0xffff0000, v147
	v_lshlrev_b32_e32 v64, 16, v148
	v_and_b32_e32 v65, 0xffff0000, v148
	v_lshlrev_b32_e32 v66, 16, v149
	v_and_b32_e32 v67, 0xffff0000, v149
